# grid barrier: the first workgroup of each XCD to arrive starts an early L2 write-back (buffer_wbl2) so the last arriver has less to flush; on top of v44
# speedup vs baseline: 1.0051x; 1.0041x over previous
; __device__ __forceinline__ unsigned xb_ld(unsigned* p)              { return __hip_atomic_load(p, __ATOMIC_RELAXED, __HIP_MEMORY_SCOPE_AGENT); }
; __device__ __forceinline__ unsigned xb_add(unsigned* p, unsigned v) { return __hip_atomic_fetch_add(p, v, __ATOMIC_RELAXED, __HIP_MEMORY_SCOPE_AGENT); }
; #define XB_SPIN(cond, bar) do { unsigned _sp = 0; while (cond) { __builtin_amdgcn_s_sleep(1); \
;     if ((++_sp & 255u) == 0u) { if (xb_ld(&(bar)[XB_TMO])) break; if (_sp > XB_SPIN_CAP) { atomicAdd(&(bar)[XB_TMO], 1u); break; } } } } while (0)
; __device__ __forceinline__ void xcd_barrier(const XcdBarrier& b) {
;     ...
;         const unsigned old = xb_add(&bar[XB_XSUB(b.x)], 1u);
;         const unsigned gen = old / nloc;
;         if (old + 1u == (gen + 1u) * nloc) {
;             __builtin_amdgcn_fence(__ATOMIC_RELEASE, "agent");
;             asm volatile("s_waitcnt vmcnt(0)" ::: "memory");
;             const unsigned og = xb_add(&bar[XB_TOP], 1u);
;             const unsigned tg = og / nx;
;             if (og + 1u == (tg + 1u) * nx) xb_add(&bar[XB_TOPGEN], 1u);
;             else XB_SPIN(xb_ld(&bar[XB_TOPGEN]) == tg, bar);
;             __builtin_amdgcn_fence(__ATOMIC_ACQUIRE, "agent");
;             xb_add(&bar[XB_XGEN(b.x)], 1u);
;             asm volatile("s_waitcnt vmcnt(0)" ::: "memory");
;         } else {
;             XB_SPIN(xb_ld(&bar[XB_XGEN(b.x)]) == gen, bar);
.LBB9_169:
	v_readlane_b32 s4, v254, 45
	v_readlane_b32 s5, v254, 46
	v_cvt_f32_u32_e32 v3, v4
	v_sub_u32_e32 v6, 0, v4
	v_rcp_iflag_f32_e32 v3, v3
	s_nop 1
	global_atomic_add v5, v187, v1, s[4:5] sc0
	v_mul_f32_e32 v3, 0x4f7ffffe, v3
	v_cvt_u32_f32_e32 v3, v3
	v_mul_lo_u32 v6, v6, v3
	v_mul_hi_u32 v6, v3, v6
	v_add_u32_e32 v3, v3, v6
	s_waitcnt vmcnt(0)
	v_mul_hi_u32 v3, v5, v3
	v_mul_lo_u32 v6, v3, v4
	v_sub_u32_e32 v6, v5, v6
	v_add_u32_e32 v7, 1, v3
	v_cmp_ge_u32_e32 vcc, v6, v4
	v_add_u32_e32 v5, 1, v5
	s_nop 0
	v_cndmask_b32_e32 v3, v3, v7, vcc
	v_sub_u32_e32 v7, v6, v4
	v_cndmask_b32_e32 v6, v6, v7, vcc
	v_add_u32_e32 v7, 1, v3
	v_cmp_ge_u32_e32 vcc, v6, v4
	s_nop 1
	v_cndmask_b32_e32 v3, v3, v7, vcc
	v_mul_lo_u32 v6, v4, v3
	v_add_u32_e32 v4, v6, v4
	v_cmp_ne_u32_e32 vcc, v5, v4
	s_and_saveexec_b64 s[4:5], vcc
	s_xor_b64 s[10:11], exec, s[4:5]
	s_cbranch_execz .LBB9_183
	v_add_u32_e32 v7, 1, v6
	v_cmp_eq_u32_e32 vcc, v5, v7
	s_cbranch_vccz .Lewb_1
	buffer_wbl2 sc1
.Lewb_1:
	v_readlane_b32 s4, v254, 51
	v_readlane_b32 s5, v254, 52
	s_waitcnt lgkmcnt(0)
	s_nop 3
	global_load_dword v2, v187, s[4:5] sc1
	s_waitcnt vmcnt(0)
	v_cmp_eq_u32_e32 vcc, v2, v3
	s_and_saveexec_b64 s[14:15], vcc
	s_cbranch_execz .LBB9_182
	s_mov_b32 s4, 1
	s_mov_b64 s[18:19], 0
	s_branch .LBB9_173

; __device__ __forceinline__ unsigned xb_ld(unsigned* p)              { return __hip_atomic_load(p, __ATOMIC_RELAXED, __HIP_MEMORY_SCOPE_AGENT); }
; __device__ __forceinline__ unsigned xb_add(unsigned* p, unsigned v) { return __hip_atomic_fetch_add(p, v, __ATOMIC_RELAXED, __HIP_MEMORY_SCOPE_AGENT); }
; #define XB_SPIN(cond, bar) do { unsigned _sp = 0; while (cond) { __builtin_amdgcn_s_sleep(1); \
;     if ((++_sp & 255u) == 0u) { if (xb_ld(&(bar)[XB_TMO])) break; if (_sp > XB_SPIN_CAP) { atomicAdd(&(bar)[XB_TMO], 1u); break; } } } } while (0)
; __device__ __forceinline__ void xcd_barrier(const XcdBarrier& b) {
;     ...
;         const unsigned old = xb_add(&bar[XB_XSUB(b.x)], 1u);
;         const unsigned gen = old / nloc;
;         if (old + 1u == (gen + 1u) * nloc) {
;             __builtin_amdgcn_fence(__ATOMIC_RELEASE, "agent");
;             asm volatile("s_waitcnt vmcnt(0)" ::: "memory");
;             const unsigned og = xb_add(&bar[XB_TOP], 1u);
;             const unsigned tg = og / nx;
;             if (og + 1u == (tg + 1u) * nx) xb_add(&bar[XB_TOPGEN], 1u);
;             else XB_SPIN(xb_ld(&bar[XB_TOPGEN]) == tg, bar);
;             __builtin_amdgcn_fence(__ATOMIC_ACQUIRE, "agent");
;             xb_add(&bar[XB_XGEN(b.x)], 1u);
;             asm volatile("s_waitcnt vmcnt(0)" ::: "memory");
;         } else {
;             XB_SPIN(xb_ld(&bar[XB_XGEN(b.x)]) == gen, bar);
.LBB9_1689:
	v_readlane_b32 s4, v254, 45
	v_readlane_b32 s5, v254, 46
	v_cvt_f32_u32_e32 v3, v4
	v_sub_u32_e32 v6, 0, v4
	v_rcp_iflag_f32_e32 v3, v3
	s_nop 1
	global_atomic_add v5, v187, v1, s[4:5] sc0
	v_mul_f32_e32 v3, 0x4f7ffffe, v3
	v_cvt_u32_f32_e32 v3, v3
	v_mul_lo_u32 v6, v6, v3
	v_mul_hi_u32 v6, v3, v6
	v_add_u32_e32 v3, v3, v6
	s_waitcnt vmcnt(0)
	v_mul_hi_u32 v3, v5, v3
	v_mul_lo_u32 v6, v3, v4
	v_sub_u32_e32 v6, v5, v6
	v_add_u32_e32 v7, 1, v3
	v_cmp_ge_u32_e32 vcc, v6, v4
	v_add_u32_e32 v5, 1, v5
	s_nop 0
	v_cndmask_b32_e32 v3, v3, v7, vcc
	v_sub_u32_e32 v7, v6, v4
	v_cndmask_b32_e32 v6, v6, v7, vcc
	v_add_u32_e32 v7, 1, v3
	v_cmp_ge_u32_e32 vcc, v6, v4
	s_nop 1
	v_cndmask_b32_e32 v3, v3, v7, vcc
	v_mul_lo_u32 v6, v4, v3
	v_add_u32_e32 v4, v6, v4
	v_cmp_ne_u32_e32 vcc, v5, v4
	s_and_saveexec_b64 s[4:5], vcc
	s_xor_b64 s[14:15], exec, s[4:5]
	s_cbranch_execz .LBB9_1703
	v_add_u32_e32 v7, 1, v6
	v_cmp_eq_u32_e32 vcc, v5, v7
	s_cbranch_vccz .Lewb_11
	buffer_wbl2 sc1
.Lewb_11:
	v_readlane_b32 s4, v254, 51
	v_readlane_b32 s5, v254, 52
	s_waitcnt lgkmcnt(0)
	s_nop 3
	global_load_dword v2, v187, s[4:5] sc1
	s_waitcnt vmcnt(0)
	v_cmp_eq_u32_e32 vcc, v2, v3
	s_and_saveexec_b64 s[18:19], vcc
	s_cbranch_execz .LBB9_1702
	s_mov_b32 s4, 1
	s_mov_b64 s[20:21], 0
	s_branch .LBB9_1693
